# m9 + residual-epilogue H loads of the down GEMM issued up front + W_in epilogue row-statistics loads issued up front
# speedup vs baseline: 1.0216x; 1.0076x over previous
; __device__ __forceinline__ unsigned cvt_pk_bf16(float lo, float hi) { unsigned r; asm volatile("v_cvt_pk_bf16_f32 %0, %1, %2" : "=v"(r) : "v"(lo), "v"(hi)); return r; }
; __device__ __forceinline__ unsigned pk4_fp8(float a, float b, float c, float d) { int w = 0; w = __builtin_amdgcn_cvt_pk_fp8_f32(clamp8(a), clamp8(b), w, false); w = __builtin_amdgcn_cvt_pk_fp8_f32(clamp8(c), clamp8(d), w, true); return (unsigned)w; }
; __device__ __forceinline__ float bf_lo(unsigned u) { return __uint_as_float(u << 16); }
; __device__ __forceinline__ float bf_hi(unsigned u) { return __uint_as_float(u & 0xffff0000u); }
;     __device__ __forceinline__ void operator()(const f32x4 (&acc)[2][2][4][2], const Unit& u, int wr, int wc, int fr, int fq) const {
;         const int row0 = u.pm * BM + wr * 64 + fr, col0 = u.pn * BM + wc * 32 + 8 * fq;
; #pragma unroll
;         for (int ai = 0; ai < 2; ++ai)
; #pragma unroll
;             for (int m = 0; m < 4; ++m) { const int row = row0 + ai * HALF + m * 16; float ss = 0.f;
; #pragma unroll
;                 for (int bj = 0; bj < 2; ++bj) { bf16_t* p = H + (size_t)row * D + col0 + bj * HALF; const u32x4 hv = *(const u32x4*)p;
;                     const f32x4 a0 = acc[ai][bj][m][0] * asc, a1 = acc[ai][bj][m][1] * asc;
;                     const float v0 = bf_lo(hv.x) + a0[0], v1 = bf_hi(hv.x) + a0[1], v2 = bf_lo(hv.y) + a0[2], v3 = bf_hi(hv.y) + a0[3];
;                     const float v4 = bf_lo(hv.z) + a1[0], v5 = bf_hi(hv.z) + a1[1], v6 = bf_lo(hv.w) + a1[2], v7 = bf_hi(hv.w) + a1[3];
;                     ss += (v0 * v0 + v1 * v1) + (v2 * v2 + v3 * v3) + (v4 * v4 + v5 * v5) + (v6 * v6 + v7 * v7);
;                     u32x4 w; w.x = cvt_pk_bf16(v0, v1); w.y = cvt_pk_bf16(v2, v3); w.z = cvt_pk_bf16(v4, v5); w.w = cvt_pk_bf16(v6, v7);
;                     *(u32x4*)p = w;
;                     if (H8) { u32x2 w8; w8.x = pk4_fp8(v0, v1, v2, v3); w8.y = pk4_fp8(v4, v5, v6, v7); *(u32x2*)(H8 + (size_t)row * D + col0 + bj * HALF) = w8; } }
.LBB0_316:
	s_nop 15
	s_nop 7
	v_lshl_add_u32 v4, s43, 8, v183
	v_ashrrev_i32_e32 v5, 31, v4
	v_lshl_or_b32 v0, s33, 8, v185
	v_lshlrev_b64 v[2:3], 11, v[4:5]
	v_ashrrev_i32_e32 v1, 31, v0
	v_lshl_add_u64 v[2:3], s[46:47], 0, v[2:3]
	v_lshl_add_u64 v[2:3], v[0:1], 1, v[2:3]
	global_load_dwordx4 v[6:9], v[2:3], off
	v_add_co_u32_e32 v174, vcc, 0x8000, v2
	s_nop 1
	v_addc_co_u32_e32 v175, vcc, 0, v3, vcc
	global_load_dwordx4 v[178:181], v[174:175], off offset:256
	global_load_dwordx4 v[174:177], v[174:175], off
	v_add_co_u32_e32 v188, vcc, 0x10000, v2
	s_nop 1
	v_addc_co_u32_e32 v189, vcc, 0, v3, vcc
	global_load_dwordx4 v[192:195], v[188:189], off offset:256
	global_load_dwordx4 v[188:191], v[188:189], off
	v_add_co_u32_e32 v218, vcc, 0x18000, v2
	s_nop 1
	v_addc_co_u32_e32 v219, vcc, 0, v3, vcc
	global_load_dwordx4 v[222:225], v[218:219], off offset:256
	global_load_dwordx4 v[218:221], v[218:219], off
	v_add_co_u32_e32 v226, vcc, 0x40000, v2
	s_nop 1
	v_addc_co_u32_e32 v227, vcc, 0, v3, vcc
	global_load_dwordx4 v[230:233], v[226:227], off offset:256
	global_load_dwordx4 v[226:229], v[226:227], off
	v_add_co_u32_e32 v234, vcc, 0x48000, v2
	s_nop 1
	v_addc_co_u32_e32 v235, vcc, 0, v3, vcc
	global_load_dwordx4 v[238:241], v[234:235], off offset:256
	global_load_dwordx4 v[234:237], v[234:235], off
	v_add_co_u32_e32 v242, vcc, 0x50000, v2
	s_nop 1
	v_addc_co_u32_e32 v243, vcc, 0, v3, vcc
	global_load_dwordx4 v[246:249], v[242:243], off offset:256
	global_load_dwordx4 v[242:245], v[242:243], off
	v_add_co_u32_e32 v250, vcc, 0x58000, v2
	s_nop 1
	v_addc_co_u32_e32 v251, vcc, 0, v3, vcc
	global_load_dwordx4 v[198:201], v[250:251], off offset:256
	global_load_dwordx4 v[250:253], v[250:251], off
	v_cndmask_b32_e64 v12, 0, 1, s[16:17]
	v_cmp_ne_u32_e64 s[14:15], 1, v12
	v_lshlrev_b64 v[12:13], 10, v[4:5]
	v_pk_mul_f32 v[16:17], v[158:159], s[96:97] op_sel_hi:[1,0]
	v_pk_mul_f32 v[10:11], v[156:157], s[96:97] op_sel_hi:[1,0]
	v_pk_mul_f32 v[18:19], v[154:155], s[96:97] op_sel_hi:[1,0]
	v_pk_mul_f32 v[20:21], v[152:153], s[96:97] op_sel_hi:[1,0]
	v_lshl_add_u64 v[22:23], s[66:67], 0, v[12:13]
	s_andn2_b64 vcc, exec, s[16:17]
	s_waitcnt vmcnt(14)
	v_lshlrev_b32_e32 v12, 16, v6
	v_and_b32_e32 v6, 0xffff0000, v6
	v_lshlrev_b32_e32 v13, 16, v7
	v_and_b32_e32 v7, 0xffff0000, v7
	v_lshlrev_b32_e32 v24, 16, v8
	v_and_b32_e32 v8, 0xffff0000, v8
	v_lshlrev_b32_e32 v25, 16, v9
	v_and_b32_e32 v26, 0xffff0000, v9
	v_add_f32_e32 v12, v10, v12
	v_add_f32_e32 v15, v11, v6
	v_add_f32_e32 v11, v16, v13
	v_add_f32_e32 v14, v17, v7
	v_add_f32_e32 v9, v20, v24
	v_add_f32_e32 v13, v21, v8
	v_add_f32_e32 v8, v18, v25
	v_add_f32_e32 v10, v19, v26
	v_lshl_add_u64 v[6:7], v[22:23], 0, v[0:1]
	v_cvt_pk_bf16_f32 v16, v12, v15
	v_cvt_pk_bf16_f32 v17, v11, v14
	v_cvt_pk_bf16_f32 v18, v9, v13
	v_cvt_pk_bf16_f32 v19, v8, v10
	global_store_dwordx4 v[2:3], v[16:19], off
	s_cbranch_vccnz .LBB0_318
	s_nop 0
	v_max_f32_e32 v16, v12, v12
	v_med3_f32 v17, v16, s38, v210
	v_max_f32_e32 v16, v15, v15
	v_med3_f32 v18, v16, s38, v210
	v_mov_b32_e32 v16, v161
	v_cvt_pk_fp8_f32 v16, v17, v18
	v_max_f32_e32 v17, v11, v11
	v_max_f32_e32 v18, v14, v14
	v_med3_f32 v17, v17, s38, v210
	v_med3_f32 v18, v18, s38, v210
	v_cvt_pk_fp8_f32 v16, v17, v18 op_sel:[0,0,1]
	v_max_f32_e32 v17, v9, v9
	v_med3_f32 v18, v17, s38, v210
	v_max_f32_e32 v17, v13, v13
	v_med3_f32 v19, v17, s38, v210
	v_mov_b32_e32 v17, v161
	v_cvt_pk_fp8_f32 v17, v18, v19
	v_max_f32_e32 v18, v8, v8
	v_max_f32_e32 v19, v10, v10
	v_med3_f32 v18, v18, s38, v210
	v_med3_f32 v19, v19, s38, v210
	v_cvt_pk_fp8_f32 v17, v18, v19 op_sel:[0,0,1]
	global_store_dwordx2 v[6:7], v[16:17], off

; __device__ __forceinline__ unsigned cvt_pk_bf16(float lo, float hi) { unsigned r; asm volatile("v_cvt_pk_bf16_f32 %0, %1, %2" : "=v"(r) : "v"(lo), "v"(hi)); return r; }
; __device__ __forceinline__ unsigned pk4_fp8(float a, float b, float c, float d) { int w = 0; w = __builtin_amdgcn_cvt_pk_fp8_f32(clamp8(a), clamp8(b), w, false); w = __builtin_amdgcn_cvt_pk_fp8_f32(clamp8(c), clamp8(d), w, true); return (unsigned)w; }
; __device__ __forceinline__ float bf_lo(unsigned u) { return __uint_as_float(u << 16); }
; __device__ __forceinline__ float bf_hi(unsigned u) { return __uint_as_float(u & 0xffff0000u); }
;     __device__ __forceinline__ void operator()(const f32x4 (&acc)[2][2][4][2], const Unit& u, int wr, int wc, int fr, int fq) const {
;     ...
;             for (int m = 0; m < 4; ++m) { const int row = row0 + ai * HALF + m * 16; float ss = 0.f;
; #pragma unroll
;                 for (int bj = 0; bj < 2; ++bj) { bf16_t* p = H + (size_t)row * D + col0 + bj * HALF; const u32x4 hv = *(const u32x4*)p;
;                     const f32x4 a0 = acc[ai][bj][m][0] * asc, a1 = acc[ai][bj][m][1] * asc;
;                     const float v0 = bf_lo(hv.x) + a0[0], v1 = bf_hi(hv.x) + a0[1], v2 = bf_lo(hv.y) + a0[2], v3 = bf_hi(hv.y) + a0[3];
;                     const float v4 = bf_lo(hv.z) + a1[0], v5 = bf_hi(hv.z) + a1[1], v6 = bf_lo(hv.w) + a1[2], v7 = bf_hi(hv.w) + a1[3];
;                     ss += (v0 * v0 + v1 * v1) + (v2 * v2 + v3 * v3) + (v4 * v4 + v5 * v5) + (v6 * v6 + v7 * v7);
;                     u32x4 w; w.x = cvt_pk_bf16(v0, v1); w.y = cvt_pk_bf16(v2, v3); w.z = cvt_pk_bf16(v4, v5); w.w = cvt_pk_bf16(v6, v7);
;                     *(u32x4*)p = w;
;                     if (H8) { u32x2 w8; w8.x = pk4_fp8(v0, v1, v2, v3); w8.y = pk4_fp8(v4, v5, v6, v7); *(u32x2*)(H8 + (size_t)row * D + col0 + bj * HALF) = w8; } }
.LBB0_322:
	s_or_b64 exec, exec, s[36:37]
	v_or_b32_e32 v6, 16, v4
	s_waitcnt lgkmcnt(0)
	v_ashrrev_i32_e32 v7, 31, v6
	v_lshlrev_b64 v[8:9], 10, v[6:7]
	v_lshlrev_b64 v[6:7], 11, v[6:7]
	v_lshl_add_u64 v[6:7], s[46:47], 0, v[6:7]
	v_lshl_add_u64 v[6:7], v[0:1], 1, v[6:7]
	s_nop 1
	v_pk_mul_f32 v[14:15], v[140:141], s[96:97] op_sel_hi:[1,0]
	v_pk_mul_f32 v[12:13], v[142:143], s[96:97] op_sel_hi:[1,0]
	v_pk_mul_f32 v[22:23], v[136:137], s[96:97] op_sel_hi:[1,0]
	v_pk_mul_f32 v[20:21], v[138:139], s[96:97] op_sel_hi:[1,0]
	v_lshl_add_u64 v[8:9], s[66:67], 0, v[8:9]
	s_and_b64 vcc, exec, s[14:15]
	v_lshl_add_u64 v[8:9], v[8:9], 0, v[0:1]
	v_lshlrev_b32_e32 v5, 16, v174
	v_add_f32_e32 v5, v14, v5
	v_and_b32_e32 v14, 0xffff0000, v174
	v_add_f32_e32 v15, v15, v14
	v_lshlrev_b32_e32 v14, 16, v175
	v_add_f32_e32 v12, v12, v14
	v_and_b32_e32 v14, 0xffff0000, v175
	v_add_f32_e32 v16, v13, v14
	v_and_b32_e32 v14, 0xffff0000, v176
	v_lshlrev_b32_e32 v13, 16, v176
	v_add_f32_e32 v17, v23, v14
	v_lshlrev_b32_e32 v14, 16, v177
	v_and_b32_e32 v18, 0xffff0000, v177
	v_add_f32_e32 v13, v22, v13
	v_add_f32_e32 v14, v20, v14
	v_add_f32_e32 v18, v21, v18
	v_cvt_pk_bf16_f32 v20, v5, v15
	v_cvt_pk_bf16_f32 v21, v12, v16
	v_cvt_pk_bf16_f32 v22, v13, v17
	v_cvt_pk_bf16_f32 v23, v14, v18
	global_store_dwordx4 v[6:7], v[20:23], off
	s_cbranch_vccnz .LBB0_324
	v_max_f32_e32 v19, v5, v5
	v_max_f32_e32 v20, v15, v15
	v_med3_f32 v19, v19, s38, v210
	v_med3_f32 v21, v20, s38, v210
	v_mov_b32_e32 v20, v161
	v_cvt_pk_fp8_f32 v20, v19, v21
	v_max_f32_e32 v19, v12, v12
	v_max_f32_e32 v21, v16, v16
	v_med3_f32 v19, v19, s38, v210
	v_med3_f32 v21, v21, s38, v210
	v_cvt_pk_fp8_f32 v20, v19, v21 op_sel:[0,0,1]
	v_max_f32_e32 v19, v13, v13
	v_max_f32_e32 v21, v17, v17
	v_med3_f32 v19, v19, s38, v210
	v_med3_f32 v22, v21, s38, v210
	v_mov_b32_e32 v21, v161
	v_cvt_pk_fp8_f32 v21, v19, v22
	v_max_f32_e32 v19, v14, v14
	v_max_f32_e32 v22, v18, v18
	v_med3_f32 v19, v19, s38, v210
	v_med3_f32 v22, v22, s38, v210
	v_cvt_pk_fp8_f32 v21, v19, v22 op_sel:[0,0,1]
	global_store_dwordx2 v[8:9], v[20:21], off
.LBB0_324:
	s_nop 1
	v_pk_mul_f32 v[20:21], v[132:133], s[96:97] op_sel_hi:[1,0]
	v_pk_mul_f32 v[22:23], v[134:135], s[96:97] op_sel_hi:[1,0]
	v_pk_mul_f32 v[28:29], v[130:131], s[96:97] op_sel_hi:[1,0]
	v_pk_mul_f32 v[30:31], v[128:129], s[96:97] op_sel_hi:[1,0]
	s_and_b64 vcc, exec, s[14:15]
	v_lshlrev_b32_e32 v19, 16, v178
	v_add_f32_e32 v19, v20, v19
	v_and_b32_e32 v20, 0xffff0000, v178
	v_add_f32_e32 v20, v21, v20
	v_lshlrev_b32_e32 v21, 16, v179
	v_add_f32_e32 v21, v22, v21
	v_and_b32_e32 v22, 0xffff0000, v179
	v_add_f32_e32 v22, v23, v22
	v_lshlrev_b32_e32 v23, 16, v180
	v_and_b32_e32 v24, 0xffff0000, v180
	v_lshlrev_b32_e32 v25, 16, v181
	v_and_b32_e32 v26, 0xffff0000, v181
	v_add_f32_e32 v23, v30, v23
	v_add_f32_e32 v24, v31, v24
	v_add_f32_e32 v25, v28, v25
	v_add_f32_e32 v26, v29, v26
	v_cvt_pk_bf16_f32 v28, v19, v20
	v_cvt_pk_bf16_f32 v29, v21, v22
	v_cvt_pk_bf16_f32 v30, v23, v24
	v_cvt_pk_bf16_f32 v31, v25, v26
	global_store_dwordx4 v[6:7], v[28:31], off offset:256
	s_cbranch_vccnz .LBB0_326
	v_max_f32_e32 v6, v19, v19
	v_med3_f32 v7, v6, s38, v210
	v_max_f32_e32 v6, v20, v20
	v_med3_f32 v27, v6, s38, v210
	v_mov_b32_e32 v6, v161
	v_cvt_pk_fp8_f32 v6, v7, v27
	v_max_f32_e32 v7, v21, v21
	v_max_f32_e32 v27, v22, v22
	v_med3_f32 v7, v7, s38, v210
	v_med3_f32 v27, v27, s38, v210
	v_cvt_pk_fp8_f32 v6, v7, v27 op_sel:[0,0,1]
	v_max_f32_e32 v7, v23, v23
	v_med3_f32 v27, v7, s38, v210
	v_max_f32_e32 v7, v24, v24
	v_med3_f32 v28, v7, s38, v210
	v_mov_b32_e32 v7, v161
	v_cvt_pk_fp8_f32 v7, v27, v28
	v_max_f32_e32 v27, v25, v25
	v_max_f32_e32 v28, v26, v26
	v_med3_f32 v27, v27, s38, v210
	v_med3_f32 v28, v28, s38, v210
	v_cvt_pk_fp8_f32 v7, v27, v28 op_sel:[0,0,1]
	global_store_dwordx2 v[8:9], v[6:7], off offset:128

; __device__ __forceinline__ unsigned cvt_pk_bf16(float lo, float hi) { unsigned r; asm volatile("v_cvt_pk_bf16_f32 %0, %1, %2" : "=v"(r) : "v"(lo), "v"(hi)); return r; }
; __device__ __forceinline__ unsigned pk4_fp8(float a, float b, float c, float d) { int w = 0; w = __builtin_amdgcn_cvt_pk_fp8_f32(clamp8(a), clamp8(b), w, false); w = __builtin_amdgcn_cvt_pk_fp8_f32(clamp8(c), clamp8(d), w, true); return (unsigned)w; }
; __device__ __forceinline__ float bf_lo(unsigned u) { return __uint_as_float(u << 16); }
; __device__ __forceinline__ float bf_hi(unsigned u) { return __uint_as_float(u & 0xffff0000u); }
;     __device__ __forceinline__ void operator()(const f32x4 (&acc)[2][2][4][2], const Unit& u, int wr, int wc, int fr, int fq) const {
;     ...
;             for (int m = 0; m < 4; ++m) { const int row = row0 + ai * HALF + m * 16; float ss = 0.f;
; #pragma unroll
;                 for (int bj = 0; bj < 2; ++bj) { bf16_t* p = H + (size_t)row * D + col0 + bj * HALF; const u32x4 hv = *(const u32x4*)p;
;                     const f32x4 a0 = acc[ai][bj][m][0] * asc, a1 = acc[ai][bj][m][1] * asc;
;                     const float v0 = bf_lo(hv.x) + a0[0], v1 = bf_hi(hv.x) + a0[1], v2 = bf_lo(hv.y) + a0[2], v3 = bf_hi(hv.y) + a0[3];
;                     const float v4 = bf_lo(hv.z) + a1[0], v5 = bf_hi(hv.z) + a1[1], v6 = bf_lo(hv.w) + a1[2], v7 = bf_hi(hv.w) + a1[3];
;                     ss += (v0 * v0 + v1 * v1) + (v2 * v2 + v3 * v3) + (v4 * v4 + v5 * v5) + (v6 * v6 + v7 * v7);
;                     u32x4 w; w.x = cvt_pk_bf16(v0, v1); w.y = cvt_pk_bf16(v2, v3); w.z = cvt_pk_bf16(v4, v5); w.w = cvt_pk_bf16(v6, v7);
;                     *(u32x4*)p = w;
;                     if (H8) { u32x2 w8; w8.x = pk4_fp8(v0, v1, v2, v3); w8.y = pk4_fp8(v4, v5, v6, v7); *(u32x2*)(H8 + (size_t)row * D + col0 + bj * HALF) = w8; } }
.LBB0_328:
	s_or_b64 exec, exec, s[36:37]
	s_waitcnt lgkmcnt(0)
	v_or_b32_e32 v6, 32, v4
	v_ashrrev_i32_e32 v7, 31, v6
	v_lshlrev_b64 v[8:9], 10, v[6:7]
	v_lshlrev_b64 v[6:7], 11, v[6:7]
	v_lshl_add_u64 v[6:7], s[46:47], 0, v[6:7]
	v_lshl_add_u64 v[6:7], v[0:1], 1, v[6:7]
	s_nop 1
	v_pk_mul_f32 v[14:15], v[124:125], s[96:97] op_sel_hi:[1,0]
	v_pk_mul_f32 v[12:13], v[126:127], s[96:97] op_sel_hi:[1,0]
	v_pk_mul_f32 v[22:23], v[120:121], s[96:97] op_sel_hi:[1,0]
	v_pk_mul_f32 v[20:21], v[122:123], s[96:97] op_sel_hi:[1,0]
	v_lshl_add_u64 v[8:9], s[66:67], 0, v[8:9]
	s_and_b64 vcc, exec, s[14:15]
	v_lshl_add_u64 v[8:9], v[8:9], 0, v[0:1]
	v_lshlrev_b32_e32 v5, 16, v188
	v_add_f32_e32 v5, v14, v5
	v_and_b32_e32 v14, 0xffff0000, v188
	v_add_f32_e32 v15, v15, v14
	v_lshlrev_b32_e32 v14, 16, v189
	v_add_f32_e32 v12, v12, v14
	v_and_b32_e32 v14, 0xffff0000, v189
	v_add_f32_e32 v16, v13, v14
	v_and_b32_e32 v14, 0xffff0000, v190
	v_lshlrev_b32_e32 v13, 16, v190
	v_add_f32_e32 v17, v23, v14
	v_lshlrev_b32_e32 v14, 16, v191
	v_and_b32_e32 v18, 0xffff0000, v191
	v_add_f32_e32 v13, v22, v13
	v_add_f32_e32 v14, v20, v14
	v_add_f32_e32 v18, v21, v18
	v_cvt_pk_bf16_f32 v20, v5, v15
	v_cvt_pk_bf16_f32 v21, v12, v16
	v_cvt_pk_bf16_f32 v22, v13, v17
	v_cvt_pk_bf16_f32 v23, v14, v18
	global_store_dwordx4 v[6:7], v[20:23], off
	s_cbranch_vccnz .LBB0_330
	v_max_f32_e32 v19, v5, v5
	v_max_f32_e32 v20, v15, v15
	v_med3_f32 v19, v19, s38, v210
	v_med3_f32 v21, v20, s38, v210
	v_mov_b32_e32 v20, v161
	v_cvt_pk_fp8_f32 v20, v19, v21
	v_max_f32_e32 v19, v12, v12
	v_max_f32_e32 v21, v16, v16
	v_med3_f32 v19, v19, s38, v210
	v_med3_f32 v21, v21, s38, v210
	v_cvt_pk_fp8_f32 v20, v19, v21 op_sel:[0,0,1]
	v_max_f32_e32 v19, v13, v13
	v_max_f32_e32 v21, v17, v17
	v_med3_f32 v19, v19, s38, v210
	v_med3_f32 v22, v21, s38, v210
	v_mov_b32_e32 v21, v161
	v_cvt_pk_fp8_f32 v21, v19, v22
	v_max_f32_e32 v19, v14, v14
	v_max_f32_e32 v22, v18, v18
	v_med3_f32 v19, v19, s38, v210
	v_med3_f32 v22, v22, s38, v210
	v_cvt_pk_fp8_f32 v21, v19, v22 op_sel:[0,0,1]
	global_store_dwordx2 v[8:9], v[20:21], off
.LBB0_330:
	s_nop 1
	v_pk_mul_f32 v[20:21], v[116:117], s[96:97] op_sel_hi:[1,0]
	v_pk_mul_f32 v[22:23], v[118:119], s[96:97] op_sel_hi:[1,0]
	v_pk_mul_f32 v[28:29], v[114:115], s[96:97] op_sel_hi:[1,0]
	v_pk_mul_f32 v[30:31], v[112:113], s[96:97] op_sel_hi:[1,0]
	s_and_b64 vcc, exec, s[14:15]
	v_lshlrev_b32_e32 v19, 16, v192
	v_add_f32_e32 v19, v20, v19
	v_and_b32_e32 v20, 0xffff0000, v192
	v_add_f32_e32 v20, v21, v20
	v_lshlrev_b32_e32 v21, 16, v193
	v_add_f32_e32 v21, v22, v21
	v_and_b32_e32 v22, 0xffff0000, v193
	v_add_f32_e32 v22, v23, v22
	v_lshlrev_b32_e32 v23, 16, v194
	v_and_b32_e32 v24, 0xffff0000, v194
	v_lshlrev_b32_e32 v25, 16, v195
	v_and_b32_e32 v26, 0xffff0000, v195
	v_add_f32_e32 v23, v30, v23
	v_add_f32_e32 v24, v31, v24
	v_add_f32_e32 v25, v28, v25
	v_add_f32_e32 v26, v29, v26
	v_cvt_pk_bf16_f32 v28, v19, v20
	v_cvt_pk_bf16_f32 v29, v21, v22
	v_cvt_pk_bf16_f32 v30, v23, v24
	v_cvt_pk_bf16_f32 v31, v25, v26
	global_store_dwordx4 v[6:7], v[28:31], off offset:256
	s_cbranch_vccnz .LBB0_332
	v_max_f32_e32 v6, v19, v19
	v_med3_f32 v7, v6, s38, v210
	v_max_f32_e32 v6, v20, v20
	v_med3_f32 v27, v6, s38, v210
	v_mov_b32_e32 v6, v161
	v_cvt_pk_fp8_f32 v6, v7, v27
	v_max_f32_e32 v7, v21, v21
	v_max_f32_e32 v27, v22, v22
	v_med3_f32 v7, v7, s38, v210
	v_med3_f32 v27, v27, s38, v210
	v_cvt_pk_fp8_f32 v6, v7, v27 op_sel:[0,0,1]
	v_max_f32_e32 v7, v23, v23
	v_med3_f32 v27, v7, s38, v210
	v_max_f32_e32 v7, v24, v24
	v_med3_f32 v28, v7, s38, v210
	v_mov_b32_e32 v7, v161
	v_cvt_pk_fp8_f32 v7, v27, v28
	v_max_f32_e32 v27, v25, v25
	v_max_f32_e32 v28, v26, v26
	v_med3_f32 v27, v27, s38, v210
	v_med3_f32 v28, v28, s38, v210
	v_cvt_pk_fp8_f32 v7, v27, v28 op_sel:[0,0,1]
	global_store_dwordx2 v[8:9], v[6:7], off offset:128

; __device__ __forceinline__ unsigned cvt_pk_bf16(float lo, float hi) { unsigned r; asm volatile("v_cvt_pk_bf16_f32 %0, %1, %2" : "=v"(r) : "v"(lo), "v"(hi)); return r; }
; __device__ __forceinline__ unsigned pk4_fp8(float a, float b, float c, float d) { int w = 0; w = __builtin_amdgcn_cvt_pk_fp8_f32(clamp8(a), clamp8(b), w, false); w = __builtin_amdgcn_cvt_pk_fp8_f32(clamp8(c), clamp8(d), w, true); return (unsigned)w; }
; __device__ __forceinline__ float bf_lo(unsigned u) { return __uint_as_float(u << 16); }
; __device__ __forceinline__ float bf_hi(unsigned u) { return __uint_as_float(u & 0xffff0000u); }
;     __device__ __forceinline__ void operator()(const f32x4 (&acc)[2][2][4][2], const Unit& u, int wr, int wc, int fr, int fq) const {
;     ...
;             for (int m = 0; m < 4; ++m) { const int row = row0 + ai * HALF + m * 16; float ss = 0.f;
; #pragma unroll
;                 for (int bj = 0; bj < 2; ++bj) { bf16_t* p = H + (size_t)row * D + col0 + bj * HALF; const u32x4 hv = *(const u32x4*)p;
;                     const f32x4 a0 = acc[ai][bj][m][0] * asc, a1 = acc[ai][bj][m][1] * asc;
;                     const float v0 = bf_lo(hv.x) + a0[0], v1 = bf_hi(hv.x) + a0[1], v2 = bf_lo(hv.y) + a0[2], v3 = bf_hi(hv.y) + a0[3];
;                     const float v4 = bf_lo(hv.z) + a1[0], v5 = bf_hi(hv.z) + a1[1], v6 = bf_lo(hv.w) + a1[2], v7 = bf_hi(hv.w) + a1[3];
;                     ss += (v0 * v0 + v1 * v1) + (v2 * v2 + v3 * v3) + (v4 * v4 + v5 * v5) + (v6 * v6 + v7 * v7);
;                     u32x4 w; w.x = cvt_pk_bf16(v0, v1); w.y = cvt_pk_bf16(v2, v3); w.z = cvt_pk_bf16(v4, v5); w.w = cvt_pk_bf16(v6, v7);
;                     *(u32x4*)p = w;
;                     if (H8) { u32x2 w8; w8.x = pk4_fp8(v0, v1, v2, v3); w8.y = pk4_fp8(v4, v5, v6, v7); *(u32x2*)(H8 + (size_t)row * D + col0 + bj * HALF) = w8; } }
.LBB0_334:
	s_or_b64 exec, exec, s[36:37]
	s_waitcnt lgkmcnt(0)
	v_or_b32_e32 v6, 48, v4
	v_ashrrev_i32_e32 v7, 31, v6
	v_lshlrev_b64 v[8:9], 10, v[6:7]
	v_lshlrev_b64 v[6:7], 11, v[6:7]
	v_lshl_add_u64 v[6:7], s[46:47], 0, v[6:7]
	v_lshl_add_u64 v[6:7], v[0:1], 1, v[6:7]
	s_nop 1
	v_pk_mul_f32 v[14:15], v[108:109], s[96:97] op_sel_hi:[1,0]
	v_pk_mul_f32 v[12:13], v[110:111], s[96:97] op_sel_hi:[1,0]
	v_pk_mul_f32 v[22:23], v[104:105], s[96:97] op_sel_hi:[1,0]
	v_pk_mul_f32 v[20:21], v[106:107], s[96:97] op_sel_hi:[1,0]
	v_lshl_add_u64 v[8:9], s[66:67], 0, v[8:9]
	s_and_b64 vcc, exec, s[14:15]
	v_lshl_add_u64 v[8:9], v[8:9], 0, v[0:1]
	v_lshlrev_b32_e32 v5, 16, v218
	v_add_f32_e32 v5, v14, v5
	v_and_b32_e32 v14, 0xffff0000, v218
	v_add_f32_e32 v15, v15, v14
	v_lshlrev_b32_e32 v14, 16, v219
	v_add_f32_e32 v12, v12, v14
	v_and_b32_e32 v14, 0xffff0000, v219
	v_add_f32_e32 v16, v13, v14
	v_and_b32_e32 v14, 0xffff0000, v220
	v_lshlrev_b32_e32 v13, 16, v220
	v_add_f32_e32 v17, v23, v14
	v_lshlrev_b32_e32 v14, 16, v221
	v_and_b32_e32 v18, 0xffff0000, v221
	v_add_f32_e32 v13, v22, v13
	v_add_f32_e32 v14, v20, v14
	v_add_f32_e32 v18, v21, v18
	v_cvt_pk_bf16_f32 v20, v5, v15
	v_cvt_pk_bf16_f32 v21, v12, v16
	v_cvt_pk_bf16_f32 v22, v13, v17
	v_cvt_pk_bf16_f32 v23, v14, v18
	global_store_dwordx4 v[6:7], v[20:23], off
	s_cbranch_vccnz .LBB0_336
	v_max_f32_e32 v19, v5, v5
	v_max_f32_e32 v20, v15, v15
	v_med3_f32 v19, v19, s38, v210
	v_med3_f32 v21, v20, s38, v210
	v_mov_b32_e32 v20, v161
	v_cvt_pk_fp8_f32 v20, v19, v21
	v_max_f32_e32 v19, v12, v12
	v_max_f32_e32 v21, v16, v16
	v_med3_f32 v19, v19, s38, v210
	v_med3_f32 v21, v21, s38, v210
	v_cvt_pk_fp8_f32 v20, v19, v21 op_sel:[0,0,1]
	v_max_f32_e32 v19, v13, v13
	v_max_f32_e32 v21, v17, v17
	v_med3_f32 v19, v19, s38, v210
	v_med3_f32 v22, v21, s38, v210
	v_mov_b32_e32 v21, v161
	v_cvt_pk_fp8_f32 v21, v19, v22
	v_max_f32_e32 v19, v14, v14
	v_max_f32_e32 v22, v18, v18
	v_med3_f32 v19, v19, s38, v210
	v_med3_f32 v22, v22, s38, v210
	v_cvt_pk_fp8_f32 v21, v19, v22 op_sel:[0,0,1]
	global_store_dwordx2 v[8:9], v[20:21], off
.LBB0_336:
	s_nop 1
	v_pk_mul_f32 v[20:21], v[100:101], s[96:97] op_sel_hi:[1,0]
	v_pk_mul_f32 v[22:23], v[102:103], s[96:97] op_sel_hi:[1,0]
	v_pk_mul_f32 v[28:29], v[98:99], s[96:97] op_sel_hi:[1,0]
	v_pk_mul_f32 v[30:31], v[96:97], s[96:97] op_sel_hi:[1,0]
	s_and_b64 vcc, exec, s[14:15]
	v_lshlrev_b32_e32 v19, 16, v222
	v_add_f32_e32 v19, v20, v19
	v_and_b32_e32 v20, 0xffff0000, v222
	v_add_f32_e32 v20, v21, v20
	v_lshlrev_b32_e32 v21, 16, v223
	v_add_f32_e32 v21, v22, v21
	v_and_b32_e32 v22, 0xffff0000, v223
	v_add_f32_e32 v22, v23, v22
	v_lshlrev_b32_e32 v23, 16, v224
	v_and_b32_e32 v24, 0xffff0000, v224
	v_lshlrev_b32_e32 v25, 16, v225
	v_and_b32_e32 v26, 0xffff0000, v225
	v_add_f32_e32 v23, v30, v23
	v_add_f32_e32 v24, v31, v24
	v_add_f32_e32 v25, v28, v25
	v_add_f32_e32 v26, v29, v26
	v_cvt_pk_bf16_f32 v28, v19, v20
	v_cvt_pk_bf16_f32 v29, v21, v22
	v_cvt_pk_bf16_f32 v30, v23, v24
	v_cvt_pk_bf16_f32 v31, v25, v26
	global_store_dwordx4 v[6:7], v[28:31], off offset:256
	s_cbranch_vccnz .LBB0_338
	v_max_f32_e32 v6, v19, v19
	v_med3_f32 v7, v6, s38, v210
	v_max_f32_e32 v6, v20, v20
	v_med3_f32 v27, v6, s38, v210
	v_mov_b32_e32 v6, v161
	v_cvt_pk_fp8_f32 v6, v7, v27
	v_max_f32_e32 v7, v21, v21
	v_max_f32_e32 v27, v22, v22
	v_med3_f32 v7, v7, s38, v210
	v_med3_f32 v27, v27, s38, v210
	v_cvt_pk_fp8_f32 v6, v7, v27 op_sel:[0,0,1]
	v_max_f32_e32 v7, v23, v23
	v_med3_f32 v27, v7, s38, v210
	v_max_f32_e32 v7, v24, v24
	v_med3_f32 v28, v7, s38, v210
	v_mov_b32_e32 v7, v161
	v_cvt_pk_fp8_f32 v7, v27, v28
	v_max_f32_e32 v27, v25, v25
	v_max_f32_e32 v28, v26, v26
	v_med3_f32 v27, v27, s38, v210
	v_med3_f32 v28, v28, s38, v210
	v_cvt_pk_fp8_f32 v7, v27, v28 op_sel:[0,0,1]
	global_store_dwordx2 v[8:9], v[6:7], off offset:128

; __device__ __forceinline__ unsigned cvt_pk_bf16(float lo, float hi) { unsigned r; asm volatile("v_cvt_pk_bf16_f32 %0, %1, %2" : "=v"(r) : "v"(lo), "v"(hi)); return r; }
; __device__ __forceinline__ unsigned pk4_fp8(float a, float b, float c, float d) { int w = 0; w = __builtin_amdgcn_cvt_pk_fp8_f32(clamp8(a), clamp8(b), w, false); w = __builtin_amdgcn_cvt_pk_fp8_f32(clamp8(c), clamp8(d), w, true); return (unsigned)w; }
; __device__ __forceinline__ float bf_lo(unsigned u) { return __uint_as_float(u << 16); }
; __device__ __forceinline__ float bf_hi(unsigned u) { return __uint_as_float(u & 0xffff0000u); }
;     __device__ __forceinline__ void operator()(const f32x4 (&acc)[2][2][4][2], const Unit& u, int wr, int wc, int fr, int fq) const {
;     ...
;             for (int m = 0; m < 4; ++m) { const int row = row0 + ai * HALF + m * 16; float ss = 0.f;
; #pragma unroll
;                 for (int bj = 0; bj < 2; ++bj) { bf16_t* p = H + (size_t)row * D + col0 + bj * HALF; const u32x4 hv = *(const u32x4*)p;
;                     const f32x4 a0 = acc[ai][bj][m][0] * asc, a1 = acc[ai][bj][m][1] * asc;
;                     const float v0 = bf_lo(hv.x) + a0[0], v1 = bf_hi(hv.x) + a0[1], v2 = bf_lo(hv.y) + a0[2], v3 = bf_hi(hv.y) + a0[3];
;                     const float v4 = bf_lo(hv.z) + a1[0], v5 = bf_hi(hv.z) + a1[1], v6 = bf_lo(hv.w) + a1[2], v7 = bf_hi(hv.w) + a1[3];
;                     ss += (v0 * v0 + v1 * v1) + (v2 * v2 + v3 * v3) + (v4 * v4 + v5 * v5) + (v6 * v6 + v7 * v7);
;                     u32x4 w; w.x = cvt_pk_bf16(v0, v1); w.y = cvt_pk_bf16(v2, v3); w.z = cvt_pk_bf16(v4, v5); w.w = cvt_pk_bf16(v6, v7);
;                     *(u32x4*)p = w;
;                     if (H8) { u32x2 w8; w8.x = pk4_fp8(v0, v1, v2, v3); w8.y = pk4_fp8(v4, v5, v6, v7); *(u32x2*)(H8 + (size_t)row * D + col0 + bj * HALF) = w8; } }
.LBB0_340:
	s_or_b64 exec, exec, s[36:37]
	s_waitcnt lgkmcnt(0)
	v_add_u32_e32 v6, 0x80, v4
	v_ashrrev_i32_e32 v7, 31, v6
	v_lshlrev_b64 v[8:9], 10, v[6:7]
	v_lshlrev_b64 v[6:7], 11, v[6:7]
	v_lshl_add_u64 v[6:7], s[46:47], 0, v[6:7]
	v_lshl_add_u64 v[6:7], v[0:1], 1, v[6:7]
	s_nop 1
	v_pk_mul_f32 v[14:15], v[92:93], s[96:97] op_sel_hi:[1,0]
	v_pk_mul_f32 v[12:13], v[94:95], s[96:97] op_sel_hi:[1,0]
	v_pk_mul_f32 v[22:23], v[88:89], s[96:97] op_sel_hi:[1,0]
	v_pk_mul_f32 v[20:21], v[90:91], s[96:97] op_sel_hi:[1,0]
	v_lshl_add_u64 v[8:9], s[66:67], 0, v[8:9]
	s_and_b64 vcc, exec, s[14:15]
	v_lshl_add_u64 v[8:9], v[8:9], 0, v[0:1]
	v_lshlrev_b32_e32 v5, 16, v226
	v_add_f32_e32 v5, v14, v5
	v_and_b32_e32 v14, 0xffff0000, v226
	v_add_f32_e32 v15, v15, v14
	v_lshlrev_b32_e32 v14, 16, v227
	v_add_f32_e32 v12, v12, v14
	v_and_b32_e32 v14, 0xffff0000, v227
	v_add_f32_e32 v16, v13, v14
	v_and_b32_e32 v14, 0xffff0000, v228
	v_lshlrev_b32_e32 v13, 16, v228
	v_add_f32_e32 v17, v23, v14
	v_lshlrev_b32_e32 v14, 16, v229
	v_and_b32_e32 v18, 0xffff0000, v229
	v_add_f32_e32 v13, v22, v13
	v_add_f32_e32 v14, v20, v14
	v_add_f32_e32 v18, v21, v18
	v_cvt_pk_bf16_f32 v20, v5, v15
	v_cvt_pk_bf16_f32 v21, v12, v16
	v_cvt_pk_bf16_f32 v22, v13, v17
	v_cvt_pk_bf16_f32 v23, v14, v18
	global_store_dwordx4 v[6:7], v[20:23], off
	s_cbranch_vccnz .LBB0_342
	v_max_f32_e32 v19, v5, v5
	v_max_f32_e32 v20, v15, v15
	v_med3_f32 v19, v19, s38, v210
	v_med3_f32 v21, v20, s38, v210
	v_mov_b32_e32 v20, v161
	v_cvt_pk_fp8_f32 v20, v19, v21
	v_max_f32_e32 v19, v12, v12
	v_max_f32_e32 v21, v16, v16
	v_med3_f32 v19, v19, s38, v210
	v_med3_f32 v21, v21, s38, v210
	v_cvt_pk_fp8_f32 v20, v19, v21 op_sel:[0,0,1]
	v_max_f32_e32 v19, v13, v13
	v_max_f32_e32 v21, v17, v17
	v_med3_f32 v19, v19, s38, v210
	v_med3_f32 v22, v21, s38, v210
	v_mov_b32_e32 v21, v161
	v_cvt_pk_fp8_f32 v21, v19, v22
	v_max_f32_e32 v19, v14, v14
	v_max_f32_e32 v22, v18, v18
	v_med3_f32 v19, v19, s38, v210
	v_med3_f32 v22, v22, s38, v210
	v_cvt_pk_fp8_f32 v21, v19, v22 op_sel:[0,0,1]
	global_store_dwordx2 v[8:9], v[20:21], off
.LBB0_342:
	s_nop 1
	v_pk_mul_f32 v[20:21], v[84:85], s[96:97] op_sel_hi:[1,0]
	v_pk_mul_f32 v[22:23], v[86:87], s[96:97] op_sel_hi:[1,0]
	v_pk_mul_f32 v[28:29], v[82:83], s[96:97] op_sel_hi:[1,0]
	v_pk_mul_f32 v[30:31], v[80:81], s[96:97] op_sel_hi:[1,0]
	s_and_b64 vcc, exec, s[14:15]
	v_lshlrev_b32_e32 v19, 16, v230
	v_add_f32_e32 v19, v20, v19
	v_and_b32_e32 v20, 0xffff0000, v230
	v_add_f32_e32 v20, v21, v20
	v_lshlrev_b32_e32 v21, 16, v231
	v_add_f32_e32 v21, v22, v21
	v_and_b32_e32 v22, 0xffff0000, v231
	v_add_f32_e32 v22, v23, v22
	v_lshlrev_b32_e32 v23, 16, v232
	v_and_b32_e32 v24, 0xffff0000, v232
	v_lshlrev_b32_e32 v25, 16, v233
	v_and_b32_e32 v26, 0xffff0000, v233
	v_add_f32_e32 v23, v30, v23
	v_add_f32_e32 v24, v31, v24
	v_add_f32_e32 v25, v28, v25
	v_add_f32_e32 v26, v29, v26
	v_cvt_pk_bf16_f32 v28, v19, v20
	v_cvt_pk_bf16_f32 v29, v21, v22
	v_cvt_pk_bf16_f32 v30, v23, v24
	v_cvt_pk_bf16_f32 v31, v25, v26
	global_store_dwordx4 v[6:7], v[28:31], off offset:256
	s_cbranch_vccnz .LBB0_344
	v_max_f32_e32 v6, v19, v19
	v_med3_f32 v7, v6, s38, v210
	v_max_f32_e32 v6, v20, v20
	v_med3_f32 v27, v6, s38, v210
	v_mov_b32_e32 v6, v161
	v_cvt_pk_fp8_f32 v6, v7, v27
	v_max_f32_e32 v7, v21, v21
	v_max_f32_e32 v27, v22, v22
	v_med3_f32 v7, v7, s38, v210
	v_med3_f32 v27, v27, s38, v210
	v_cvt_pk_fp8_f32 v6, v7, v27 op_sel:[0,0,1]
	v_max_f32_e32 v7, v23, v23
	v_med3_f32 v27, v7, s38, v210
	v_max_f32_e32 v7, v24, v24
	v_med3_f32 v28, v7, s38, v210
	v_mov_b32_e32 v7, v161
	v_cvt_pk_fp8_f32 v7, v27, v28
	v_max_f32_e32 v27, v25, v25
	v_max_f32_e32 v28, v26, v26
	v_med3_f32 v27, v27, s38, v210
	v_med3_f32 v28, v28, s38, v210
	v_cvt_pk_fp8_f32 v7, v27, v28 op_sel:[0,0,1]
	global_store_dwordx2 v[8:9], v[6:7], off offset:128

; __device__ __forceinline__ unsigned cvt_pk_bf16(float lo, float hi) { unsigned r; asm volatile("v_cvt_pk_bf16_f32 %0, %1, %2" : "=v"(r) : "v"(lo), "v"(hi)); return r; }
; __device__ __forceinline__ unsigned pk4_fp8(float a, float b, float c, float d) { int w = 0; w = __builtin_amdgcn_cvt_pk_fp8_f32(clamp8(a), clamp8(b), w, false); w = __builtin_amdgcn_cvt_pk_fp8_f32(clamp8(c), clamp8(d), w, true); return (unsigned)w; }
; __device__ __forceinline__ float bf_lo(unsigned u) { return __uint_as_float(u << 16); }
; __device__ __forceinline__ float bf_hi(unsigned u) { return __uint_as_float(u & 0xffff0000u); }
;     __device__ __forceinline__ void operator()(const f32x4 (&acc)[2][2][4][2], const Unit& u, int wr, int wc, int fr, int fq) const {
;     ...
;             for (int m = 0; m < 4; ++m) { const int row = row0 + ai * HALF + m * 16; float ss = 0.f;
; #pragma unroll
;                 for (int bj = 0; bj < 2; ++bj) { bf16_t* p = H + (size_t)row * D + col0 + bj * HALF; const u32x4 hv = *(const u32x4*)p;
;                     const f32x4 a0 = acc[ai][bj][m][0] * asc, a1 = acc[ai][bj][m][1] * asc;
;                     const float v0 = bf_lo(hv.x) + a0[0], v1 = bf_hi(hv.x) + a0[1], v2 = bf_lo(hv.y) + a0[2], v3 = bf_hi(hv.y) + a0[3];
;                     const float v4 = bf_lo(hv.z) + a1[0], v5 = bf_hi(hv.z) + a1[1], v6 = bf_lo(hv.w) + a1[2], v7 = bf_hi(hv.w) + a1[3];
;                     ss += (v0 * v0 + v1 * v1) + (v2 * v2 + v3 * v3) + (v4 * v4 + v5 * v5) + (v6 * v6 + v7 * v7);
;                     u32x4 w; w.x = cvt_pk_bf16(v0, v1); w.y = cvt_pk_bf16(v2, v3); w.z = cvt_pk_bf16(v4, v5); w.w = cvt_pk_bf16(v6, v7);
;                     *(u32x4*)p = w;
;                     if (H8) { u32x2 w8; w8.x = pk4_fp8(v0, v1, v2, v3); w8.y = pk4_fp8(v4, v5, v6, v7); *(u32x2*)(H8 + (size_t)row * D + col0 + bj * HALF) = w8; } }
.LBB0_346:
	s_or_b64 exec, exec, s[36:37]
	s_waitcnt lgkmcnt(0)
	v_add_u32_e32 v6, 0x90, v4
	v_ashrrev_i32_e32 v7, 31, v6
	v_lshlrev_b64 v[8:9], 10, v[6:7]
	v_lshlrev_b64 v[6:7], 11, v[6:7]
	v_lshl_add_u64 v[6:7], s[46:47], 0, v[6:7]
	v_lshl_add_u64 v[6:7], v[0:1], 1, v[6:7]
	s_nop 1
	v_pk_mul_f32 v[14:15], v[76:77], s[96:97] op_sel_hi:[1,0]
	v_pk_mul_f32 v[12:13], v[78:79], s[96:97] op_sel_hi:[1,0]
	v_pk_mul_f32 v[22:23], v[72:73], s[96:97] op_sel_hi:[1,0]
	v_pk_mul_f32 v[20:21], v[74:75], s[96:97] op_sel_hi:[1,0]
	v_lshl_add_u64 v[8:9], s[66:67], 0, v[8:9]
	s_and_b64 vcc, exec, s[14:15]
	v_lshl_add_u64 v[8:9], v[8:9], 0, v[0:1]
	v_lshlrev_b32_e32 v5, 16, v234
	v_add_f32_e32 v5, v14, v5
	v_and_b32_e32 v14, 0xffff0000, v234
	v_add_f32_e32 v15, v15, v14
	v_lshlrev_b32_e32 v14, 16, v235
	v_add_f32_e32 v12, v12, v14
	v_and_b32_e32 v14, 0xffff0000, v235
	v_add_f32_e32 v16, v13, v14
	v_and_b32_e32 v14, 0xffff0000, v236
	v_lshlrev_b32_e32 v13, 16, v236
	v_add_f32_e32 v17, v23, v14
	v_lshlrev_b32_e32 v14, 16, v237
	v_and_b32_e32 v18, 0xffff0000, v237
	v_add_f32_e32 v13, v22, v13
	v_add_f32_e32 v14, v20, v14
	v_add_f32_e32 v18, v21, v18
	v_cvt_pk_bf16_f32 v20, v5, v15
	v_cvt_pk_bf16_f32 v21, v12, v16
	v_cvt_pk_bf16_f32 v22, v13, v17
	v_cvt_pk_bf16_f32 v23, v14, v18
	global_store_dwordx4 v[6:7], v[20:23], off
	s_cbranch_vccnz .LBB0_348
	v_max_f32_e32 v19, v5, v5
	v_max_f32_e32 v20, v15, v15
	v_med3_f32 v19, v19, s38, v210
	v_med3_f32 v21, v20, s38, v210
	v_mov_b32_e32 v20, v161
	v_cvt_pk_fp8_f32 v20, v19, v21
	v_max_f32_e32 v19, v12, v12
	v_max_f32_e32 v21, v16, v16
	v_med3_f32 v19, v19, s38, v210
	v_med3_f32 v21, v21, s38, v210
	v_cvt_pk_fp8_f32 v20, v19, v21 op_sel:[0,0,1]
	v_max_f32_e32 v19, v13, v13
	v_max_f32_e32 v21, v17, v17
	v_med3_f32 v19, v19, s38, v210
	v_med3_f32 v22, v21, s38, v210
	v_mov_b32_e32 v21, v161
	v_cvt_pk_fp8_f32 v21, v19, v22
	v_max_f32_e32 v19, v14, v14
	v_max_f32_e32 v22, v18, v18
	v_med3_f32 v19, v19, s38, v210
	v_med3_f32 v22, v22, s38, v210
	v_cvt_pk_fp8_f32 v21, v19, v22 op_sel:[0,0,1]
	global_store_dwordx2 v[8:9], v[20:21], off
.LBB0_348:
	s_nop 1
	v_pk_mul_f32 v[20:21], v[68:69], s[96:97] op_sel_hi:[1,0]
	v_pk_mul_f32 v[22:23], v[70:71], s[96:97] op_sel_hi:[1,0]
	v_pk_mul_f32 v[28:29], v[66:67], s[96:97] op_sel_hi:[1,0]
	v_pk_mul_f32 v[30:31], v[64:65], s[96:97] op_sel_hi:[1,0]
	s_and_b64 vcc, exec, s[14:15]
	v_lshlrev_b32_e32 v19, 16, v238
	v_add_f32_e32 v19, v20, v19
	v_and_b32_e32 v20, 0xffff0000, v238
	v_add_f32_e32 v20, v21, v20
	v_lshlrev_b32_e32 v21, 16, v239
	v_add_f32_e32 v21, v22, v21
	v_and_b32_e32 v22, 0xffff0000, v239
	v_add_f32_e32 v22, v23, v22
	v_lshlrev_b32_e32 v23, 16, v240
	v_and_b32_e32 v24, 0xffff0000, v240
	v_lshlrev_b32_e32 v25, 16, v241
	v_and_b32_e32 v26, 0xffff0000, v241
	v_add_f32_e32 v23, v30, v23
	v_add_f32_e32 v24, v31, v24
	v_add_f32_e32 v25, v28, v25
	v_add_f32_e32 v26, v29, v26
	v_cvt_pk_bf16_f32 v28, v19, v20
	v_cvt_pk_bf16_f32 v29, v21, v22
	v_cvt_pk_bf16_f32 v30, v23, v24
	v_cvt_pk_bf16_f32 v31, v25, v26
	global_store_dwordx4 v[6:7], v[28:31], off offset:256
	s_cbranch_vccnz .LBB0_350
	v_max_f32_e32 v6, v19, v19
	v_med3_f32 v7, v6, s38, v210
	v_max_f32_e32 v6, v20, v20
	v_med3_f32 v27, v6, s38, v210
	v_mov_b32_e32 v6, v161
	v_cvt_pk_fp8_f32 v6, v7, v27
	v_max_f32_e32 v7, v21, v21
	v_max_f32_e32 v27, v22, v22
	v_med3_f32 v7, v7, s38, v210
	v_med3_f32 v27, v27, s38, v210
	v_cvt_pk_fp8_f32 v6, v7, v27 op_sel:[0,0,1]
	v_max_f32_e32 v7, v23, v23
	v_med3_f32 v27, v7, s38, v210
	v_max_f32_e32 v7, v24, v24
	v_med3_f32 v28, v7, s38, v210
	v_mov_b32_e32 v7, v161
	v_cvt_pk_fp8_f32 v7, v27, v28
	v_max_f32_e32 v27, v25, v25
	v_max_f32_e32 v28, v26, v26
	v_med3_f32 v27, v27, s38, v210
	v_med3_f32 v28, v28, s38, v210
	v_cvt_pk_fp8_f32 v7, v27, v28 op_sel:[0,0,1]
	global_store_dwordx2 v[8:9], v[6:7], off offset:128

; __device__ __forceinline__ unsigned cvt_pk_bf16(float lo, float hi) { unsigned r; asm volatile("v_cvt_pk_bf16_f32 %0, %1, %2" : "=v"(r) : "v"(lo), "v"(hi)); return r; }
; __device__ __forceinline__ unsigned pk4_fp8(float a, float b, float c, float d) { int w = 0; w = __builtin_amdgcn_cvt_pk_fp8_f32(clamp8(a), clamp8(b), w, false); w = __builtin_amdgcn_cvt_pk_fp8_f32(clamp8(c), clamp8(d), w, true); return (unsigned)w; }
; __device__ __forceinline__ float bf_lo(unsigned u) { return __uint_as_float(u << 16); }
; __device__ __forceinline__ float bf_hi(unsigned u) { return __uint_as_float(u & 0xffff0000u); }
;     __device__ __forceinline__ void operator()(const f32x4 (&acc)[2][2][4][2], const Unit& u, int wr, int wc, int fr, int fq) const {
;     ...
;             for (int m = 0; m < 4; ++m) { const int row = row0 + ai * HALF + m * 16; float ss = 0.f;
; #pragma unroll
;                 for (int bj = 0; bj < 2; ++bj) { bf16_t* p = H + (size_t)row * D + col0 + bj * HALF; const u32x4 hv = *(const u32x4*)p;
;                     const f32x4 a0 = acc[ai][bj][m][0] * asc, a1 = acc[ai][bj][m][1] * asc;
;                     const float v0 = bf_lo(hv.x) + a0[0], v1 = bf_hi(hv.x) + a0[1], v2 = bf_lo(hv.y) + a0[2], v3 = bf_hi(hv.y) + a0[3];
;                     const float v4 = bf_lo(hv.z) + a1[0], v5 = bf_hi(hv.z) + a1[1], v6 = bf_lo(hv.w) + a1[2], v7 = bf_hi(hv.w) + a1[3];
;                     ss += (v0 * v0 + v1 * v1) + (v2 * v2 + v3 * v3) + (v4 * v4 + v5 * v5) + (v6 * v6 + v7 * v7);
;                     u32x4 w; w.x = cvt_pk_bf16(v0, v1); w.y = cvt_pk_bf16(v2, v3); w.z = cvt_pk_bf16(v4, v5); w.w = cvt_pk_bf16(v6, v7);
;                     *(u32x4*)p = w;
;                     if (H8) { u32x2 w8; w8.x = pk4_fp8(v0, v1, v2, v3); w8.y = pk4_fp8(v4, v5, v6, v7); *(u32x2*)(H8 + (size_t)row * D + col0 + bj * HALF) = w8; } }
.LBB0_352:
	s_or_b64 exec, exec, s[36:37]
	s_waitcnt lgkmcnt(0)
	v_add_u32_e32 v6, 0xa0, v4
	v_ashrrev_i32_e32 v7, 31, v6
	v_lshlrev_b64 v[8:9], 10, v[6:7]
	v_lshlrev_b64 v[6:7], 11, v[6:7]
	v_lshl_add_u64 v[6:7], s[46:47], 0, v[6:7]
	v_lshl_add_u64 v[6:7], v[0:1], 1, v[6:7]
	s_nop 1
	v_pk_mul_f32 v[14:15], v[60:61], s[96:97] op_sel_hi:[1,0]
	v_pk_mul_f32 v[12:13], v[62:63], s[96:97] op_sel_hi:[1,0]
	v_pk_mul_f32 v[22:23], v[56:57], s[96:97] op_sel_hi:[1,0]
	v_pk_mul_f32 v[20:21], v[58:59], s[96:97] op_sel_hi:[1,0]
	v_lshl_add_u64 v[8:9], s[66:67], 0, v[8:9]
	s_and_b64 vcc, exec, s[14:15]
	v_lshl_add_u64 v[8:9], v[8:9], 0, v[0:1]
	v_lshlrev_b32_e32 v5, 16, v242
	v_add_f32_e32 v5, v14, v5
	v_and_b32_e32 v14, 0xffff0000, v242
	v_add_f32_e32 v15, v15, v14
	v_lshlrev_b32_e32 v14, 16, v243
	v_add_f32_e32 v12, v12, v14
	v_and_b32_e32 v14, 0xffff0000, v243
	v_add_f32_e32 v16, v13, v14
	v_and_b32_e32 v14, 0xffff0000, v244
	v_lshlrev_b32_e32 v13, 16, v244
	v_add_f32_e32 v17, v23, v14
	v_lshlrev_b32_e32 v14, 16, v245
	v_and_b32_e32 v18, 0xffff0000, v245
	v_add_f32_e32 v13, v22, v13
	v_add_f32_e32 v14, v20, v14
	v_add_f32_e32 v18, v21, v18
	v_cvt_pk_bf16_f32 v20, v5, v15
	v_cvt_pk_bf16_f32 v21, v12, v16
	v_cvt_pk_bf16_f32 v22, v13, v17
	v_cvt_pk_bf16_f32 v23, v14, v18
	global_store_dwordx4 v[6:7], v[20:23], off
	s_cbranch_vccnz .LBB0_354
	v_max_f32_e32 v19, v5, v5
	v_max_f32_e32 v20, v15, v15
	v_med3_f32 v19, v19, s38, v210
	v_med3_f32 v21, v20, s38, v210
	v_mov_b32_e32 v20, v161
	v_cvt_pk_fp8_f32 v20, v19, v21
	v_max_f32_e32 v19, v12, v12
	v_max_f32_e32 v21, v16, v16
	v_med3_f32 v19, v19, s38, v210
	v_med3_f32 v21, v21, s38, v210
	v_cvt_pk_fp8_f32 v20, v19, v21 op_sel:[0,0,1]
	v_max_f32_e32 v19, v13, v13
	v_max_f32_e32 v21, v17, v17
	v_med3_f32 v19, v19, s38, v210
	v_med3_f32 v22, v21, s38, v210
	v_mov_b32_e32 v21, v161
	v_cvt_pk_fp8_f32 v21, v19, v22
	v_max_f32_e32 v19, v14, v14
	v_max_f32_e32 v22, v18, v18
	v_med3_f32 v19, v19, s38, v210
	v_med3_f32 v22, v22, s38, v210
	v_cvt_pk_fp8_f32 v21, v19, v22 op_sel:[0,0,1]
	global_store_dwordx2 v[8:9], v[20:21], off
.LBB0_354:
	s_nop 1
	v_pk_mul_f32 v[20:21], v[52:53], s[96:97] op_sel_hi:[1,0]
	v_pk_mul_f32 v[22:23], v[54:55], s[96:97] op_sel_hi:[1,0]
	v_pk_mul_f32 v[28:29], v[50:51], s[96:97] op_sel_hi:[1,0]
	v_pk_mul_f32 v[30:31], v[48:49], s[96:97] op_sel_hi:[1,0]
	s_and_b64 vcc, exec, s[14:15]
	v_lshlrev_b32_e32 v19, 16, v246
	v_add_f32_e32 v19, v20, v19
	v_and_b32_e32 v20, 0xffff0000, v246
	v_add_f32_e32 v20, v21, v20
	v_lshlrev_b32_e32 v21, 16, v247
	v_add_f32_e32 v21, v22, v21
	v_and_b32_e32 v22, 0xffff0000, v247
	v_add_f32_e32 v22, v23, v22
	v_lshlrev_b32_e32 v23, 16, v248
	v_and_b32_e32 v24, 0xffff0000, v248
	v_lshlrev_b32_e32 v25, 16, v249
	v_and_b32_e32 v26, 0xffff0000, v249
	v_add_f32_e32 v23, v30, v23
	v_add_f32_e32 v24, v31, v24
	v_add_f32_e32 v25, v28, v25
	v_add_f32_e32 v26, v29, v26
	v_cvt_pk_bf16_f32 v28, v19, v20
	v_cvt_pk_bf16_f32 v29, v21, v22
	v_cvt_pk_bf16_f32 v30, v23, v24
	v_cvt_pk_bf16_f32 v31, v25, v26
	global_store_dwordx4 v[6:7], v[28:31], off offset:256
	s_cbranch_vccnz .LBB0_356
	v_max_f32_e32 v6, v19, v19
	v_med3_f32 v7, v6, s38, v210
	v_max_f32_e32 v6, v20, v20
	v_med3_f32 v27, v6, s38, v210
	v_mov_b32_e32 v6, v161
	v_cvt_pk_fp8_f32 v6, v7, v27
	v_max_f32_e32 v7, v21, v21
	v_max_f32_e32 v27, v22, v22
	v_med3_f32 v7, v7, s38, v210
	v_med3_f32 v27, v27, s38, v210
	v_cvt_pk_fp8_f32 v6, v7, v27 op_sel:[0,0,1]
	v_max_f32_e32 v7, v23, v23
	v_med3_f32 v27, v7, s38, v210
	v_max_f32_e32 v7, v24, v24
	v_med3_f32 v28, v7, s38, v210
	v_mov_b32_e32 v7, v161
	v_cvt_pk_fp8_f32 v7, v27, v28
	v_max_f32_e32 v27, v25, v25
	v_max_f32_e32 v28, v26, v26
	v_med3_f32 v27, v27, s38, v210
	v_med3_f32 v28, v28, s38, v210
	v_cvt_pk_fp8_f32 v7, v27, v28 op_sel:[0,0,1]
	global_store_dwordx2 v[8:9], v[6:7], off offset:128

; __device__ __forceinline__ unsigned cvt_pk_bf16(float lo, float hi) { unsigned r; asm volatile("v_cvt_pk_bf16_f32 %0, %1, %2" : "=v"(r) : "v"(lo), "v"(hi)); return r; }
; __device__ __forceinline__ unsigned pk4_fp8(float a, float b, float c, float d) { int w = 0; w = __builtin_amdgcn_cvt_pk_fp8_f32(clamp8(a), clamp8(b), w, false); w = __builtin_amdgcn_cvt_pk_fp8_f32(clamp8(c), clamp8(d), w, true); return (unsigned)w; }
; __device__ __forceinline__ float bf_lo(unsigned u) { return __uint_as_float(u << 16); }
; __device__ __forceinline__ float bf_hi(unsigned u) { return __uint_as_float(u & 0xffff0000u); }
;     __device__ __forceinline__ void operator()(const f32x4 (&acc)[2][2][4][2], const Unit& u, int wr, int wc, int fr, int fq) const {
;     ...
;             for (int m = 0; m < 4; ++m) { const int row = row0 + ai * HALF + m * 16; float ss = 0.f;
; #pragma unroll
;                 for (int bj = 0; bj < 2; ++bj) { bf16_t* p = H + (size_t)row * D + col0 + bj * HALF; const u32x4 hv = *(const u32x4*)p;
;                     const f32x4 a0 = acc[ai][bj][m][0] * asc, a1 = acc[ai][bj][m][1] * asc;
;                     const float v0 = bf_lo(hv.x) + a0[0], v1 = bf_hi(hv.x) + a0[1], v2 = bf_lo(hv.y) + a0[2], v3 = bf_hi(hv.y) + a0[3];
;                     const float v4 = bf_lo(hv.z) + a1[0], v5 = bf_hi(hv.z) + a1[1], v6 = bf_lo(hv.w) + a1[2], v7 = bf_hi(hv.w) + a1[3];
;                     ss += (v0 * v0 + v1 * v1) + (v2 * v2 + v3 * v3) + (v4 * v4 + v5 * v5) + (v6 * v6 + v7 * v7);
;                     u32x4 w; w.x = cvt_pk_bf16(v0, v1); w.y = cvt_pk_bf16(v2, v3); w.z = cvt_pk_bf16(v4, v5); w.w = cvt_pk_bf16(v6, v7);
;                     *(u32x4*)p = w;
;                     if (H8) { u32x2 w8; w8.x = pk4_fp8(v0, v1, v2, v3); w8.y = pk4_fp8(v4, v5, v6, v7); *(u32x2*)(H8 + (size_t)row * D + col0 + bj * HALF) = w8; } }
.LBB0_358:
	s_or_b64 exec, exec, s[36:37]
	v_add_u32_e32 v4, 0xb0, v4
	v_ashrrev_i32_e32 v5, 31, v4
	v_lshlrev_b64 v[20:21], 10, v[4:5]
	v_lshlrev_b64 v[4:5], 11, v[4:5]
	v_lshl_add_u64 v[4:5], s[46:47], 0, v[4:5]
	v_lshl_add_u64 v[4:5], v[0:1], 1, v[4:5]
	s_nop 1
	s_waitcnt lgkmcnt(0)
	v_pk_mul_f32 v[6:7], v[44:45], s[96:97] op_sel_hi:[1,0]
	v_pk_mul_f32 v[8:9], v[46:47], s[96:97] op_sel_hi:[1,0]
	v_pk_mul_f32 v[18:19], v[40:41], s[96:97] op_sel_hi:[1,0]
	v_pk_mul_f32 v[16:17], v[42:43], s[96:97] op_sel_hi:[1,0]
	s_and_b64 vcc, exec, s[14:15]
	v_lshlrev_b32_e32 v22, 16, v250
	v_and_b32_e32 v12, 0xffff0000, v250
	v_add_f32_e32 v12, v7, v12
	v_lshlrev_b32_e32 v7, 16, v251
	v_add_f32_e32 v7, v8, v7
	v_and_b32_e32 v8, 0xffff0000, v251
	v_add_f32_e32 v13, v9, v8
	v_and_b32_e32 v9, 0xffff0000, v252
	v_lshlrev_b32_e32 v8, 16, v252
	v_add_f32_e32 v14, v19, v9
	v_lshlrev_b32_e32 v9, 16, v253
	v_and_b32_e32 v15, 0xffff0000, v253
	v_add_f32_e32 v6, v6, v22
	v_add_f32_e32 v9, v16, v9
	v_add_f32_e32 v15, v17, v15
	v_cvt_pk_bf16_f32 v16, v6, v12
	v_cvt_pk_bf16_f32 v17, v7, v13
	v_add_f32_e32 v8, v18, v8
	v_cvt_pk_bf16_f32 v18, v8, v14
	v_cvt_pk_bf16_f32 v19, v9, v15
	global_store_dwordx4 v[4:5], v[16:19], off
	s_nop 1
	v_lshl_add_u64 v[16:17], s[66:67], 0, v[20:21]
	v_lshl_add_u64 v[0:1], v[16:17], 0, v[0:1]
	s_cbranch_vccnz .LBB0_360
	v_max_f32_e32 v16, v6, v6
	v_med3_f32 v17, v16, s38, v210
	v_max_f32_e32 v16, v12, v12
	v_med3_f32 v18, v16, s38, v210
	v_mov_b32_e32 v16, v161
	v_cvt_pk_fp8_f32 v16, v17, v18
	v_max_f32_e32 v17, v7, v7
	v_max_f32_e32 v18, v13, v13
	v_med3_f32 v17, v17, s38, v210
	v_med3_f32 v18, v18, s38, v210
	v_cvt_pk_fp8_f32 v16, v17, v18 op_sel:[0,0,1]
	v_max_f32_e32 v17, v8, v8
	v_med3_f32 v18, v17, s38, v210
	v_max_f32_e32 v17, v14, v14
	v_med3_f32 v19, v17, s38, v210
	v_mov_b32_e32 v17, v161
	v_cvt_pk_fp8_f32 v17, v18, v19
	v_max_f32_e32 v18, v9, v9
	v_max_f32_e32 v19, v15, v15
	v_med3_f32 v18, v18, s38, v210
	v_med3_f32 v19, v19, s38, v210
	v_cvt_pk_fp8_f32 v17, v18, v19 op_sel:[0,0,1]
	global_store_dwordx2 v[0:1], v[16:17], off
.LBB0_360:
	s_nop 1
	v_pk_mul_f32 v[16:17], v[36:37], s[96:97] op_sel_hi:[1,0]
	v_pk_mul_f32 v[18:19], v[38:39], s[96:97] op_sel_hi:[1,0]
	v_pk_mul_f32 v[24:25], v[34:35], s[96:97] op_sel_hi:[1,0]
	v_pk_mul_f32 v[26:27], v[32:33], s[96:97] op_sel_hi:[1,0]
	s_and_b64 vcc, exec, s[14:15]
	v_lshlrev_b32_e32 v28, 16, v198
	v_and_b32_e32 v20, 0xffff0000, v198
	v_add_f32_e32 v17, v17, v20
	v_lshlrev_b32_e32 v20, 16, v199
	v_add_f32_e32 v18, v18, v20
	v_and_b32_e32 v20, 0xffff0000, v199
	v_add_f32_e32 v19, v19, v20
	v_lshlrev_b32_e32 v20, 16, v200
	v_and_b32_e32 v21, 0xffff0000, v200
	v_lshlrev_b32_e32 v22, 16, v201
	v_and_b32_e32 v23, 0xffff0000, v201
	v_add_f32_e32 v16, v16, v28
	v_add_f32_e32 v20, v26, v20
	v_add_f32_e32 v21, v27, v21
	v_add_f32_e32 v22, v24, v22
	v_add_f32_e32 v23, v25, v23
	v_cvt_pk_bf16_f32 v24, v16, v17
	v_cvt_pk_bf16_f32 v25, v18, v19
	v_cvt_pk_bf16_f32 v26, v20, v21
	v_cvt_pk_bf16_f32 v27, v22, v23
	global_store_dwordx4 v[4:5], v[24:27], off offset:256
	s_cbranch_vccnz .LBB0_362
	v_max_f32_e32 v4, v16, v16
	v_med3_f32 v5, v4, s38, v210
	v_max_f32_e32 v4, v17, v17
	v_med3_f32 v24, v4, s38, v210
	v_mov_b32_e32 v4, v161
	v_cvt_pk_fp8_f32 v4, v5, v24
	v_max_f32_e32 v5, v18, v18
	v_max_f32_e32 v24, v19, v19
	v_med3_f32 v5, v5, s38, v210
	v_med3_f32 v24, v24, s38, v210
	v_cvt_pk_fp8_f32 v4, v5, v24 op_sel:[0,0,1]
	v_max_f32_e32 v5, v20, v20
	v_med3_f32 v24, v5, s38, v210
	v_max_f32_e32 v5, v21, v21
	v_med3_f32 v25, v5, s38, v210
	v_mov_b32_e32 v5, v161
	v_cvt_pk_fp8_f32 v5, v24, v25
	v_max_f32_e32 v24, v22, v22
	v_max_f32_e32 v25, v23, v23
	v_med3_f32 v24, v24, s38, v210
	v_med3_f32 v25, v25, s38, v210
	v_cvt_pk_fp8_f32 v5, v24, v25 op_sel:[0,0,1]
	global_store_dwordx2 v[0:1], v[4:5], off offset:128

; __device__ __forceinline__ unsigned cvt_pk_bf16(float lo, float hi) { unsigned r; asm volatile("v_cvt_pk_bf16_f32 %0, %1, %2" : "=v"(r) : "v"(lo), "v"(hi)); return r; }
; __device__ __forceinline__ float rstd_of(const unsigned long long* ssq, int row) { return rsqrtf((float)ssq[row] * (1.0f / (SSQ_SCALE * 1024.0f)) + EPS); }
;     __device__ __forceinline__ void operator()(const f32x4 (&acc)[2][2][4][2], const Unit& u, int wr, int wc, int fr, int fq) const {
;         const int row0 = u.pm * BM + wr * 64 + fr, col0 = u.pn * BM + wc * 32 + 8 * fq;
; #pragma unroll
;         for (int ai = 0; ai < 2; ++ai)
; #pragma unroll
;             for (int m = 0; m < 4; ++m) { const int row = row0 + ai * HALF + m * 16; const float rs = rstd_of(ssq, row);
; #pragma unroll
;                 for (int bj = 0; bj < 2; ++bj) { const f32x4 v0 = acc[ai][bj][m][0] * rs, v1 = acc[ai][bj][m][1] * rs;
;                     u32x4 w; w.x = cvt_pk_bf16(v0[0], v0[1]); w.y = cvt_pk_bf16(v0[2], v0[3]); w.z = cvt_pk_bf16(v1[0], v1[1]); w.w = cvt_pk_bf16(v1[2], v1[3]);
;                     *(u32x4*)(O + (size_t)row * ldc + col0 + bj * HALF) = w; } }
.LBB0_439:
	v_lshl_add_u32 v134, s43, 8, v138
	v_ashrrev_i32_e32 v135, 31, v134
	v_lshl_add_u64 v[136:137], v[134:135], 3, s[58:59]
	global_load_dwordx2 v[218:219], v[136:137], off
	global_load_dwordx2 v[220:221], v[136:137], off offset:128
	global_load_dwordx2 v[222:223], v[136:137], off offset:256
	global_load_dwordx2 v[224:225], v[136:137], off offset:384
	global_load_dwordx2 v[226:227], v[136:137], off offset:1024
	global_load_dwordx2 v[228:229], v[136:137], off offset:1152
	global_load_dwordx2 v[230:231], v[136:137], off offset:1280
	global_load_dwordx2 v[232:233], v[136:137], off offset:1408
	v_lshl_or_b32 v142, s33, 8, v140
	v_ashrrev_i32_e32 v143, 31, v142
	s_waitcnt vmcnt(0)
	v_ffbh_u32_e32 v135, v219
	v_min_u32_e32 v135, 32, v135
	v_lshlrev_b64 v[144:145], v135, v[218:219]
	v_min_u32_e32 v144, 1, v144
	v_or_b32_e32 v144, v145, v144
	v_cvt_f32_u32_e32 v144, v144
	v_sub_u32_e32 v135, 32, v135
	v_ldexp_f32 v135, v144, v135
	v_fmamk_f32 v135, v135, 0x30800000, v205
	v_cmp_gt_f32_e32 vcc, s92, v135
	v_mul_f32_e32 v144, 0x4b800000, v135
	s_nop 0
	v_cndmask_b32_e32 v135, v135, v144, vcc
	v_rsq_f32_e32 v135, v135
	s_nop 0
	v_mul_f32_e32 v144, 0x45800000, v135
	v_cndmask_b32_e32 v144, v135, v144, vcc
	v_pk_mul_f32 v[126:127], v[126:127], v[144:145] op_sel_hi:[1,0]
	v_pk_mul_f32 v[124:125], v[124:125], v[144:145] op_sel_hi:[1,0]
	v_pk_mul_f32 v[120:121], v[120:121], v[144:145] op_sel_hi:[1,0]
	v_pk_mul_f32 v[122:123], v[122:123], v[144:145] op_sel_hi:[1,0]
	v_cvt_pk_bf16_f32 v124, v124, v125
	v_cvt_pk_bf16_f32 v125, v126, v127
	v_cvt_pk_bf16_f32 v126, v120, v121
	v_mov_b64_e32 v[120:121], s[48:49]
	v_cvt_pk_bf16_f32 v127, v122, v123
	v_mad_i64_i32 v[146:147], s[24:25], v134, s69, v[120:121]
	v_lshlrev_b64 v[122:123], 1, v[142:143]
	v_lshl_add_u64 v[142:143], v[146:147], 0, v[122:123]
	global_store_dwordx4 v[142:143], v[124:127], off
	v_pk_mul_f32 v[116:117], v[116:117], v[144:145] op_sel_hi:[1,0]
	v_pk_mul_f32 v[118:119], v[118:119], v[144:145] op_sel_hi:[1,0]
	v_pk_mul_f32 v[124:125], v[114:115], v[144:145] op_sel_hi:[1,0]
	v_pk_mul_f32 v[114:115], v[112:113], v[144:145] op_sel_hi:[1,0]
	v_cvt_pk_bf16_f32 v112, v116, v117
	v_cvt_pk_bf16_f32 v113, v118, v119
	s_nop 0
	v_cvt_pk_bf16_f32 v114, v114, v115
	v_cvt_pk_bf16_f32 v115, v124, v125
	global_store_dwordx4 v[142:143], v[112:115], off offset:256
	s_nop 1
	v_or_b32_e32 v112, 16, v134
	v_ashrrev_i32_e32 v113, 31, v112
	v_lshl_add_u64 v[114:115], v[112:113], 3, s[58:59]
	s_nop 1
	v_ffbh_u32_e32 v113, v221
	v_min_u32_e32 v113, 32, v113
	v_lshlrev_b64 v[114:115], v113, v[220:221]
	v_min_u32_e32 v114, 1, v114
	v_or_b32_e32 v114, v115, v114
	v_cvt_f32_u32_e32 v114, v114
	v_sub_u32_e32 v113, 32, v113
	v_ldexp_f32 v113, v114, v113
	v_fmamk_f32 v113, v113, 0x30800000, v205
	v_cmp_gt_f32_e32 vcc, s92, v113
	v_mul_f32_e32 v114, 0x4b800000, v113
	s_nop 0
	v_cndmask_b32_e32 v113, v113, v114, vcc
	v_rsq_f32_e32 v113, v113
	s_nop 0
	v_mul_f32_e32 v114, 0x45800000, v113
	v_cndmask_b32_e32 v114, v113, v114, vcc
	v_pk_mul_f32 v[108:109], v[108:109], v[114:115] op_sel_hi:[1,0]
	v_pk_mul_f32 v[116:117], v[106:107], v[114:115] op_sel_hi:[1,0]
	v_pk_mul_f32 v[106:107], v[104:105], v[114:115] op_sel_hi:[1,0]
	v_cvt_pk_bf16_f32 v104, v108, v109
	v_mad_i64_i32 v[108:109], s[24:25], v112, s69, v[120:121]
	v_pk_mul_f32 v[110:111], v[110:111], v[114:115] op_sel_hi:[1,0]
	v_lshl_add_u64 v[108:109], v[108:109], 0, v[122:123]
	v_cvt_pk_bf16_f32 v105, v110, v111
	v_cvt_pk_bf16_f32 v106, v106, v107
	v_cvt_pk_bf16_f32 v107, v116, v117
	global_store_dwordx4 v[108:109], v[104:107], off
	v_pk_mul_f32 v[100:101], v[100:101], v[114:115] op_sel_hi:[1,0]
	v_pk_mul_f32 v[102:103], v[102:103], v[114:115] op_sel_hi:[1,0]
	v_pk_mul_f32 v[104:105], v[98:99], v[114:115] op_sel_hi:[1,0]
	v_pk_mul_f32 v[98:99], v[96:97], v[114:115] op_sel_hi:[1,0]
	v_cvt_pk_bf16_f32 v96, v100, v101
	v_cvt_pk_bf16_f32 v97, v102, v103
	s_nop 0
	v_cvt_pk_bf16_f32 v98, v98, v99
	v_cvt_pk_bf16_f32 v99, v104, v105
	global_store_dwordx4 v[108:109], v[96:99], off offset:256
	s_nop 1
	v_or_b32_e32 v96, 32, v134
	v_ashrrev_i32_e32 v97, 31, v96
	v_lshl_add_u64 v[98:99], v[96:97], 3, s[58:59]
	s_nop 1
	v_ffbh_u32_e32 v97, v223
	v_min_u32_e32 v97, 32, v97
	v_lshlrev_b64 v[98:99], v97, v[222:223]
	v_min_u32_e32 v98, 1, v98
	v_or_b32_e32 v98, v99, v98
	v_cvt_f32_u32_e32 v98, v98
	v_sub_u32_e32 v97, 32, v97
	v_ldexp_f32 v97, v98, v97
	v_fmamk_f32 v97, v97, 0x30800000, v205
	v_cmp_gt_f32_e32 vcc, s92, v97
	v_mul_f32_e32 v98, 0x4b800000, v97
	s_nop 0
	v_cndmask_b32_e32 v97, v97, v98, vcc
	v_rsq_f32_e32 v97, v97
	s_nop 0
	v_mul_f32_e32 v98, 0x45800000, v97
	v_cndmask_b32_e32 v98, v97, v98, vcc
	v_pk_mul_f32 v[92:93], v[92:93], v[98:99] op_sel_hi:[1,0]
	v_pk_mul_f32 v[100:101], v[90:91], v[98:99] op_sel_hi:[1,0]
	v_pk_mul_f32 v[90:91], v[88:89], v[98:99] op_sel_hi:[1,0]
	v_cvt_pk_bf16_f32 v88, v92, v93
	v_mad_i64_i32 v[92:93], s[24:25], v96, s69, v[120:121]
	v_pk_mul_f32 v[94:95], v[94:95], v[98:99] op_sel_hi:[1,0]
	v_lshl_add_u64 v[92:93], v[92:93], 0, v[122:123]
	v_cvt_pk_bf16_f32 v89, v94, v95
	v_cvt_pk_bf16_f32 v90, v90, v91
	v_cvt_pk_bf16_f32 v91, v100, v101
	global_store_dwordx4 v[92:93], v[88:91], off
	v_pk_mul_f32 v[84:85], v[84:85], v[98:99] op_sel_hi:[1,0]
	v_pk_mul_f32 v[86:87], v[86:87], v[98:99] op_sel_hi:[1,0]
	v_pk_mul_f32 v[88:89], v[82:83], v[98:99] op_sel_hi:[1,0]
	v_pk_mul_f32 v[82:83], v[80:81], v[98:99] op_sel_hi:[1,0]
	v_cvt_pk_bf16_f32 v80, v84, v85
	v_cvt_pk_bf16_f32 v81, v86, v87
	s_nop 0
	v_cvt_pk_bf16_f32 v82, v82, v83
	v_cvt_pk_bf16_f32 v83, v88, v89
	global_store_dwordx4 v[92:93], v[80:83], off offset:256
	s_nop 1
	v_or_b32_e32 v80, 48, v134
; __device__ __forceinline__ unsigned cvt_pk_bf16(float lo, float hi) { unsigned r; asm volatile("v_cvt_pk_bf16_f32 %0, %1, %2" : "=v"(r) : "v"(lo), "v"(hi)); return r; }
; __device__ __forceinline__ float rstd_of(const unsigned long long* ssq, int row) { return rsqrtf((float)ssq[row] * (1.0f / (SSQ_SCALE * 1024.0f)) + EPS); }
;     __device__ __forceinline__ void operator()(const f32x4 (&acc)[2][2][4][2], const Unit& u, int wr, int wc, int fr, int fq) const {
;         const int row0 = u.pm * BM + wr * 64 + fr, col0 = u.pn * BM + wc * 32 + 8 * fq;
; #pragma unroll
;         for (int ai = 0; ai < 2; ++ai)
; #pragma unroll
;             for (int m = 0; m < 4; ++m) { const int row = row0 + ai * HALF + m * 16; const float rs = rstd_of(ssq, row);
; #pragma unroll
;                 for (int bj = 0; bj < 2; ++bj) { const f32x4 v0 = acc[ai][bj][m][0] * rs, v1 = acc[ai][bj][m][1] * rs;
;                     u32x4 w; w.x = cvt_pk_bf16(v0[0], v0[1]); w.y = cvt_pk_bf16(v0[2], v0[3]); w.z = cvt_pk_bf16(v1[0], v1[1]); w.w = cvt_pk_bf16(v1[2], v1[3]);
;                     *(u32x4*)(O + (size_t)row * ldc + col0 + bj * HALF) = w; } }
	v_ashrrev_i32_e32 v81, 31, v80
	v_lshl_add_u64 v[82:83], v[80:81], 3, s[58:59]
	s_nop 1
	v_ffbh_u32_e32 v81, v225
	v_min_u32_e32 v81, 32, v81
	v_lshlrev_b64 v[82:83], v81, v[224:225]
	v_min_u32_e32 v82, 1, v82
	v_or_b32_e32 v82, v83, v82
	v_cvt_f32_u32_e32 v82, v82
	v_sub_u32_e32 v81, 32, v81
	v_ldexp_f32 v81, v82, v81
	v_fmamk_f32 v81, v81, 0x30800000, v205
	v_cmp_gt_f32_e32 vcc, s92, v81
	v_mul_f32_e32 v82, 0x4b800000, v81
	s_nop 0
	v_cndmask_b32_e32 v81, v81, v82, vcc
	v_rsq_f32_e32 v81, v81
	s_nop 0
	v_mul_f32_e32 v82, 0x45800000, v81
	v_cndmask_b32_e32 v82, v81, v82, vcc
	v_pk_mul_f32 v[76:77], v[76:77], v[82:83] op_sel_hi:[1,0]
	v_pk_mul_f32 v[84:85], v[74:75], v[82:83] op_sel_hi:[1,0]
	v_pk_mul_f32 v[74:75], v[72:73], v[82:83] op_sel_hi:[1,0]
	v_cvt_pk_bf16_f32 v72, v76, v77
	v_mad_i64_i32 v[76:77], s[24:25], v80, s69, v[120:121]
	v_pk_mul_f32 v[78:79], v[78:79], v[82:83] op_sel_hi:[1,0]
	v_lshl_add_u64 v[76:77], v[76:77], 0, v[122:123]
	v_cvt_pk_bf16_f32 v73, v78, v79
	v_cvt_pk_bf16_f32 v74, v74, v75
	v_cvt_pk_bf16_f32 v75, v84, v85
	global_store_dwordx4 v[76:77], v[72:75], off
	v_pk_mul_f32 v[70:71], v[70:71], v[82:83] op_sel_hi:[1,0]
	v_pk_mul_f32 v[68:69], v[68:69], v[82:83] op_sel_hi:[1,0]
	v_pk_mul_f32 v[72:73], v[66:67], v[82:83] op_sel_hi:[1,0]
	v_pk_mul_f32 v[66:67], v[64:65], v[82:83] op_sel_hi:[1,0]
	v_cvt_pk_bf16_f32 v64, v68, v69
	v_cvt_pk_bf16_f32 v65, v70, v71
	v_add_u32_e32 v68, 0x80, v134
	v_cvt_pk_bf16_f32 v66, v66, v67
	v_cvt_pk_bf16_f32 v67, v72, v73
	global_store_dwordx4 v[76:77], v[64:67], off offset:256
	s_nop 1
	v_ffbh_u32_e32 v66, v227
	v_min_u32_e32 v66, 32, v66
	v_lshlrev_b64 v[64:65], v66, v[226:227]
	v_min_u32_e32 v64, 1, v64
	v_or_b32_e32 v64, v65, v64
	v_cvt_f32_u32_e32 v64, v64
	v_sub_u32_e32 v65, 32, v66
	v_ldexp_f32 v64, v64, v65
	v_fmamk_f32 v64, v64, 0x30800000, v205
	v_cmp_gt_f32_e32 vcc, s92, v64
	v_mul_f32_e32 v65, 0x4b800000, v64
	s_nop 0
	v_cndmask_b32_e32 v64, v64, v65, vcc
	v_rsq_f32_e32 v64, v64
	s_nop 0
	v_mul_f32_e32 v65, 0x45800000, v64
	v_cndmask_b32_e32 v64, v64, v65, vcc
	v_pk_mul_f32 v[60:61], v[60:61], v[64:65] op_sel_hi:[1,0]
	v_pk_mul_f32 v[66:67], v[58:59], v[64:65] op_sel_hi:[1,0]
	v_pk_mul_f32 v[58:59], v[56:57], v[64:65] op_sel_hi:[1,0]
	v_cvt_pk_bf16_f32 v56, v60, v61
	v_mad_i64_i32 v[60:61], s[24:25], v68, s69, v[120:121]
	v_pk_mul_f32 v[62:63], v[62:63], v[64:65] op_sel_hi:[1,0]
	v_lshl_add_u64 v[60:61], v[60:61], 0, v[122:123]
	v_cvt_pk_bf16_f32 v57, v62, v63
	v_cvt_pk_bf16_f32 v58, v58, v59
	v_cvt_pk_bf16_f32 v59, v66, v67
	global_store_dwordx4 v[60:61], v[56:59], off
	v_pk_mul_f32 v[54:55], v[54:55], v[64:65] op_sel_hi:[1,0]
	v_pk_mul_f32 v[52:53], v[52:53], v[64:65] op_sel_hi:[1,0]
	v_pk_mul_f32 v[56:57], v[50:51], v[64:65] op_sel_hi:[1,0]
	v_pk_mul_f32 v[50:51], v[48:49], v[64:65] op_sel_hi:[1,0]
	v_cvt_pk_bf16_f32 v48, v52, v53
	v_cvt_pk_bf16_f32 v49, v54, v55
	v_add_u32_e32 v52, 0x90, v134
	v_cvt_pk_bf16_f32 v50, v50, v51
	v_cvt_pk_bf16_f32 v51, v56, v57
	global_store_dwordx4 v[60:61], v[48:51], off offset:256
	s_nop 1
	v_ffbh_u32_e32 v50, v229
	v_min_u32_e32 v50, 32, v50
	v_lshlrev_b64 v[48:49], v50, v[228:229]
	v_min_u32_e32 v48, 1, v48
	v_or_b32_e32 v48, v49, v48
	v_cvt_f32_u32_e32 v48, v48
	v_sub_u32_e32 v49, 32, v50
	v_ldexp_f32 v48, v48, v49
	v_fmamk_f32 v48, v48, 0x30800000, v205
	v_cmp_gt_f32_e32 vcc, s92, v48
	v_mul_f32_e32 v49, 0x4b800000, v48
	s_nop 0
	v_cndmask_b32_e32 v48, v48, v49, vcc
	v_rsq_f32_e32 v48, v48
	s_nop 0
	v_mul_f32_e32 v49, 0x45800000, v48
	v_cndmask_b32_e32 v48, v48, v49, vcc
	v_pk_mul_f32 v[44:45], v[44:45], v[48:49] op_sel_hi:[1,0]
	v_pk_mul_f32 v[50:51], v[42:43], v[48:49] op_sel_hi:[1,0]
	v_pk_mul_f32 v[42:43], v[40:41], v[48:49] op_sel_hi:[1,0]
	v_cvt_pk_bf16_f32 v40, v44, v45
	v_mad_i64_i32 v[44:45], s[24:25], v52, s69, v[120:121]
; __device__ __forceinline__ unsigned cvt_pk_bf16(float lo, float hi) { unsigned r; asm volatile("v_cvt_pk_bf16_f32 %0, %1, %2" : "=v"(r) : "v"(lo), "v"(hi)); return r; }
; __device__ __forceinline__ float rstd_of(const unsigned long long* ssq, int row) { return rsqrtf((float)ssq[row] * (1.0f / (SSQ_SCALE * 1024.0f)) + EPS); }
;     __device__ __forceinline__ void operator()(const f32x4 (&acc)[2][2][4][2], const Unit& u, int wr, int wc, int fr, int fq) const {
;         const int row0 = u.pm * BM + wr * 64 + fr, col0 = u.pn * BM + wc * 32 + 8 * fq;
; #pragma unroll
;         for (int ai = 0; ai < 2; ++ai)
; #pragma unroll
;             for (int m = 0; m < 4; ++m) { const int row = row0 + ai * HALF + m * 16; const float rs = rstd_of(ssq, row);
; #pragma unroll
;                 for (int bj = 0; bj < 2; ++bj) { const f32x4 v0 = acc[ai][bj][m][0] * rs, v1 = acc[ai][bj][m][1] * rs;
;                     u32x4 w; w.x = cvt_pk_bf16(v0[0], v0[1]); w.y = cvt_pk_bf16(v0[2], v0[3]); w.z = cvt_pk_bf16(v1[0], v1[1]); w.w = cvt_pk_bf16(v1[2], v1[3]);
;                     *(u32x4*)(O + (size_t)row * ldc + col0 + bj * HALF) = w; } }
;     }
	v_pk_mul_f32 v[46:47], v[46:47], v[48:49] op_sel_hi:[1,0]
	v_lshl_add_u64 v[44:45], v[44:45], 0, v[122:123]
	v_cvt_pk_bf16_f32 v41, v46, v47
	v_cvt_pk_bf16_f32 v42, v42, v43
	v_cvt_pk_bf16_f32 v43, v50, v51
	global_store_dwordx4 v[44:45], v[40:43], off
	v_pk_mul_f32 v[38:39], v[38:39], v[48:49] op_sel_hi:[1,0]
	v_pk_mul_f32 v[36:37], v[36:37], v[48:49] op_sel_hi:[1,0]
	v_pk_mul_f32 v[40:41], v[34:35], v[48:49] op_sel_hi:[1,0]
	v_pk_mul_f32 v[34:35], v[32:33], v[48:49] op_sel_hi:[1,0]
	v_cvt_pk_bf16_f32 v32, v36, v37
	v_cvt_pk_bf16_f32 v33, v38, v39
	v_add_u32_e32 v36, 0xa0, v134
	v_cvt_pk_bf16_f32 v34, v34, v35
	v_cvt_pk_bf16_f32 v35, v40, v41
	global_store_dwordx4 v[44:45], v[32:35], off offset:256
	s_nop 1
	v_ffbh_u32_e32 v34, v231
	v_min_u32_e32 v34, 32, v34
	v_lshlrev_b64 v[32:33], v34, v[230:231]
	v_min_u32_e32 v32, 1, v32
	v_or_b32_e32 v32, v33, v32
	v_cvt_f32_u32_e32 v32, v32
	v_sub_u32_e32 v33, 32, v34
	v_ldexp_f32 v32, v32, v33
	v_fmamk_f32 v32, v32, 0x30800000, v205
	v_cmp_gt_f32_e32 vcc, s92, v32
	v_mul_f32_e32 v33, 0x4b800000, v32
	s_nop 0
	v_cndmask_b32_e32 v32, v32, v33, vcc
	v_rsq_f32_e32 v32, v32
	s_nop 0
	v_mul_f32_e32 v33, 0x45800000, v32
	v_cndmask_b32_e32 v32, v32, v33, vcc
	v_pk_mul_f32 v[28:29], v[28:29], v[32:33] op_sel_hi:[1,0]
	v_pk_mul_f32 v[34:35], v[26:27], v[32:33] op_sel_hi:[1,0]
	v_pk_mul_f32 v[26:27], v[24:25], v[32:33] op_sel_hi:[1,0]
	v_cvt_pk_bf16_f32 v24, v28, v29
	v_mad_i64_i32 v[28:29], s[24:25], v36, s69, v[120:121]
	v_pk_mul_f32 v[30:31], v[30:31], v[32:33] op_sel_hi:[1,0]
	v_lshl_add_u64 v[28:29], v[28:29], 0, v[122:123]
	v_cvt_pk_bf16_f32 v25, v30, v31
	v_cvt_pk_bf16_f32 v26, v26, v27
	v_cvt_pk_bf16_f32 v27, v34, v35
	global_store_dwordx4 v[28:29], v[24:27], off
	v_pk_mul_f32 v[22:23], v[22:23], v[32:33] op_sel_hi:[1,0]
	v_pk_mul_f32 v[20:21], v[20:21], v[32:33] op_sel_hi:[1,0]
	v_pk_mul_f32 v[24:25], v[18:19], v[32:33] op_sel_hi:[1,0]
	v_pk_mul_f32 v[18:19], v[16:17], v[32:33] op_sel_hi:[1,0]
	v_cvt_pk_bf16_f32 v16, v20, v21
	v_cvt_pk_bf16_f32 v17, v22, v23
	v_add_u32_e32 v20, 0xb0, v134
	v_cvt_pk_bf16_f32 v18, v18, v19
	v_cvt_pk_bf16_f32 v19, v24, v25
	global_store_dwordx4 v[28:29], v[16:19], off offset:256
	s_nop 1
	v_ffbh_u32_e32 v18, v233
	v_min_u32_e32 v18, 32, v18
	v_lshlrev_b64 v[16:17], v18, v[232:233]
	v_min_u32_e32 v16, 1, v16
	v_or_b32_e32 v16, v17, v16
	v_cvt_f32_u32_e32 v16, v16
	v_sub_u32_e32 v17, 32, v18
	v_ldexp_f32 v16, v16, v17
	v_fmamk_f32 v16, v16, 0x30800000, v205
	v_cmp_gt_f32_e32 vcc, s92, v16
	v_mul_f32_e32 v17, 0x4b800000, v16
	s_nop 0
	v_cndmask_b32_e32 v16, v16, v17, vcc
	v_rsq_f32_e32 v16, v16
	s_nop 0
	v_mul_f32_e32 v17, 0x45800000, v16
	v_cndmask_b32_e32 v16, v16, v17, vcc
	v_pk_mul_f32 v[12:13], v[12:13], v[16:17] op_sel_hi:[1,0]
	v_pk_mul_f32 v[18:19], v[10:11], v[16:17] op_sel_hi:[1,0]
	v_pk_mul_f32 v[10:11], v[8:9], v[16:17] op_sel_hi:[1,0]
	v_cvt_pk_bf16_f32 v8, v12, v13
	v_mad_i64_i32 v[12:13], s[24:25], v20, s69, v[120:121]
	v_pk_mul_f32 v[14:15], v[14:15], v[16:17] op_sel_hi:[1,0]
	v_lshl_add_u64 v[12:13], v[12:13], 0, v[122:123]
	v_cvt_pk_bf16_f32 v9, v14, v15
	v_cvt_pk_bf16_f32 v10, v10, v11
	v_cvt_pk_bf16_f32 v11, v18, v19
	global_store_dwordx4 v[12:13], v[8:11], off
	s_mov_b64 s[24:25], -1
	s_andn2_b64 vcc, exec, s[10:11]
	v_pk_mul_f32 v[8:9], v[2:3], v[16:17] op_sel_hi:[1,0]
	v_pk_mul_f32 v[2:3], v[0:1], v[16:17] op_sel_hi:[1,0]
	v_pk_mul_f32 v[6:7], v[6:7], v[16:17] op_sel_hi:[1,0]
	v_pk_mul_f32 v[4:5], v[4:5], v[16:17] op_sel_hi:[1,0]
	s_nop 0
	v_cvt_pk_bf16_f32 v0, v4, v5
	v_cvt_pk_bf16_f32 v1, v6, v7
	v_cvt_pk_bf16_f32 v2, v2, v3
	v_cvt_pk_bf16_f32 v3, v8, v9
	global_store_dwordx4 v[12:13], v[0:3], off offset:256
	s_cbranch_vccnz .LBB0_432
	s_andn2_b64 vcc, exec, s[12:13]
	s_cbranch_vccnz .LBB0_431
	s_barrier
	s_branch .LBB0_431
